# in_proj epilogue: gate sigmoid 7->5 VALU/elem (drop redundant min, fold max into fma clamp), non-rope PXA tiles fast path (cvt+store only)
# speedup vs baseline: 1.0209x; 1.0209x over previous
.LBB0_345:
	s_and_b64 vcc, exec, s[8:9]
	s_cbranch_vccz .LBB0_366
	s_lshl_b32 s9, s87, 2
	s_add_i32 s0, s87, -16
	s_lshl_b32 s8, s88, 4
	s_and_b32 s9, s9, 12
	s_or_b32 s8, s9, s8
	s_lshr_b32 s0, s0, 2
	s_add_i32 s8, s8, s0
	s_ashr_i32 s9, s8, 31
	s_lshl_b64 s[8:9], s[8:9], 16
	v_lshl_add_u64 v[0:1], v[190:191], 0, s[8:9]
	s_mov_b64 s[8:9], 0x1000
	v_lshl_add_u64 v[26:27], v[0:1], 0, s[8:9]
	v_mul_f32_e32 v2, 0xbfb8aa3b, v162
	v_mul_f32_e32 v3, 0xbfb8aa3b, v163
	v_mul_f32_e32 v4, 0xbfb8aa3b, v164
	v_mul_f32_e32 v5, 0xbfb8aa3b, v165
	v_mul_f32_e32 v6, 0xbfb8aa3b, v158
	v_mul_f32_e32 v7, 0xbfb8aa3b, v159
	v_mul_f32_e32 v8, 0xbfb8aa3b, v160
	v_mul_f32_e32 v9, 0xbfb8aa3b, v161
	v_mul_f32_e32 v10, 0xbfb8aa3b, v154
	v_mul_f32_e32 v11, 0xbfb8aa3b, v155
	v_mul_f32_e32 v12, 0xbfb8aa3b, v156
	v_mul_f32_e32 v13, 0xbfb8aa3b, v157
	v_mul_f32_e32 v14, 0xbfb8aa3b, v150
	v_mul_f32_e32 v15, 0xbfb8aa3b, v151
	v_mul_f32_e32 v16, 0xbfb8aa3b, v152
	v_mul_f32_e32 v17, 0xbfb8aa3b, v153
	v_exp_f32_e32 v2, v2
	v_exp_f32_e32 v3, v3
	v_exp_f32_e32 v4, v4
	v_exp_f32_e32 v5, v5
	v_exp_f32_e32 v6, v6
	v_exp_f32_e32 v7, v7
	v_exp_f32_e32 v8, v8
	v_exp_f32_e32 v9, v9
	v_exp_f32_e32 v10, v10
	v_exp_f32_e32 v11, v11
	v_exp_f32_e32 v12, v12
	v_exp_f32_e32 v13, v13
	v_exp_f32_e32 v14, v14
	v_exp_f32_e32 v15, v15
	v_exp_f32_e32 v16, v16
	v_exp_f32_e32 v17, v17
	v_fma_f32 v2, v2, v217, v217 clamp
	v_fma_f32 v3, v3, v217, v217 clamp
	v_fma_f32 v4, v4, v217, v217 clamp
	v_fma_f32 v5, v5, v217, v217 clamp
	v_fma_f32 v6, v6, v217, v217 clamp
	v_fma_f32 v7, v7, v217, v217 clamp
	v_fma_f32 v8, v8, v217, v217 clamp
	v_fma_f32 v9, v9, v217, v217 clamp
	v_fma_f32 v10, v10, v217, v217 clamp
	v_fma_f32 v11, v11, v217, v217 clamp
	v_fma_f32 v12, v12, v217, v217 clamp
	v_fma_f32 v13, v13, v217, v217 clamp
	v_fma_f32 v14, v14, v217, v217 clamp
	v_fma_f32 v15, v15, v217, v217 clamp
	v_fma_f32 v16, v16, v217, v217 clamp
	v_fma_f32 v17, v17, v217, v217 clamp
	v_rcp_f32_e32 v2, v2
	v_rcp_f32_e32 v3, v3
	v_rcp_f32_e32 v4, v4
	v_rcp_f32_e32 v5, v5
	v_rcp_f32_e32 v6, v6
	v_rcp_f32_e32 v7, v7
	v_rcp_f32_e32 v8, v8
	v_rcp_f32_e32 v9, v9
	v_rcp_f32_e32 v10, v10
	v_rcp_f32_e32 v11, v11
	v_rcp_f32_e32 v12, v12
	v_rcp_f32_e32 v13, v13
	v_rcp_f32_e32 v14, v14
	v_rcp_f32_e32 v15, v15
	v_rcp_f32_e32 v16, v16
	v_rcp_f32_e32 v17, v17
	v_cvt_pk_u8_f32 v18, v2, 0, 0
	v_cvt_pk_u8_f32 v19, v6, 0, 0
	v_cvt_pk_u8_f32 v20, v10, 0, 0
	v_cvt_pk_u8_f32 v21, v14, 0, 0
	v_cvt_pk_u8_f32 v18, v3, 1, v18
	v_cvt_pk_u8_f32 v19, v7, 1, v19
	v_cvt_pk_u8_f32 v20, v11, 1, v20
	v_cvt_pk_u8_f32 v21, v15, 1, v21
	v_cvt_pk_u8_f32 v18, v4, 2, v18
	v_cvt_pk_u8_f32 v19, v8, 2, v19
	v_cvt_pk_u8_f32 v20, v12, 2, v20
	v_cvt_pk_u8_f32 v21, v16, 2, v21
	v_cvt_pk_u8_f32 v18, v5, 3, v18
	v_cvt_pk_u8_f32 v19, v9, 3, v19
	v_cvt_pk_u8_f32 v20, v13, 3, v20
	v_cvt_pk_u8_f32 v21, v17, 3, v21
	global_store_dwordx4 v[0:1], v[18:21], off nt
	v_mul_f32_e32 v2, 0xbfb8aa3b, v146
	v_mul_f32_e32 v3, 0xbfb8aa3b, v147
	v_mul_f32_e32 v4, 0xbfb8aa3b, v148
	v_mul_f32_e32 v5, 0xbfb8aa3b, v149
	v_mul_f32_e32 v6, 0xbfb8aa3b, v142
	v_mul_f32_e32 v7, 0xbfb8aa3b, v143
	v_mul_f32_e32 v8, 0xbfb8aa3b, v144
	v_mul_f32_e32 v9, 0xbfb8aa3b, v145
	v_mul_f32_e32 v10, 0xbfb8aa3b, v138
	v_mul_f32_e32 v11, 0xbfb8aa3b, v139
	v_mul_f32_e32 v12, 0xbfb8aa3b, v140
	v_mul_f32_e32 v13, 0xbfb8aa3b, v141
	v_mul_f32_e32 v14, 0xbfb8aa3b, v134
	v_mul_f32_e32 v15, 0xbfb8aa3b, v135
	v_mul_f32_e32 v16, 0xbfb8aa3b, v136
	v_mul_f32_e32 v17, 0xbfb8aa3b, v137
	v_exp_f32_e32 v2, v2
	v_exp_f32_e32 v3, v3
	v_exp_f32_e32 v4, v4
	v_exp_f32_e32 v5, v5
	v_exp_f32_e32 v6, v6
	v_exp_f32_e32 v7, v7
	v_exp_f32_e32 v8, v8
	v_exp_f32_e32 v9, v9
	v_exp_f32_e32 v10, v10
	v_exp_f32_e32 v11, v11
	v_exp_f32_e32 v12, v12
	v_exp_f32_e32 v13, v13
	v_exp_f32_e32 v14, v14
	v_exp_f32_e32 v15, v15
	v_exp_f32_e32 v16, v16
	v_exp_f32_e32 v17, v17
	v_fma_f32 v2, v2, v217, v217 clamp
	v_fma_f32 v3, v3, v217, v217 clamp
	v_fma_f32 v4, v4, v217, v217 clamp
	v_fma_f32 v5, v5, v217, v217 clamp
	v_fma_f32 v6, v6, v217, v217 clamp
	v_fma_f32 v7, v7, v217, v217 clamp
	v_fma_f32 v8, v8, v217, v217 clamp
	v_fma_f32 v9, v9, v217, v217 clamp
	v_fma_f32 v10, v10, v217, v217 clamp
	v_fma_f32 v11, v11, v217, v217 clamp
	v_fma_f32 v12, v12, v217, v217 clamp
	v_fma_f32 v13, v13, v217, v217 clamp
	v_fma_f32 v14, v14, v217, v217 clamp
	v_fma_f32 v15, v15, v217, v217 clamp
	v_fma_f32 v16, v16, v217, v217 clamp
	v_fma_f32 v17, v17, v217, v217 clamp
	v_rcp_f32_e32 v2, v2
	v_rcp_f32_e32 v3, v3
	v_rcp_f32_e32 v4, v4
	v_rcp_f32_e32 v5, v5
	v_rcp_f32_e32 v6, v6
	v_rcp_f32_e32 v7, v7
	v_rcp_f32_e32 v8, v8
	v_rcp_f32_e32 v9, v9
	v_rcp_f32_e32 v10, v10
	v_rcp_f32_e32 v11, v11
	v_rcp_f32_e32 v12, v12
	v_rcp_f32_e32 v13, v13
	v_rcp_f32_e32 v14, v14
	v_rcp_f32_e32 v15, v15
	v_rcp_f32_e32 v16, v16
	v_rcp_f32_e32 v17, v17
	v_cvt_pk_u8_f32 v22, v2, 0, 0
	v_cvt_pk_u8_f32 v23, v6, 0, 0
	v_cvt_pk_u8_f32 v24, v10, 0, 0
	v_cvt_pk_u8_f32 v25, v14, 0, 0
	v_cvt_pk_u8_f32 v22, v3, 1, v22
	v_cvt_pk_u8_f32 v23, v7, 1, v23
	v_cvt_pk_u8_f32 v24, v11, 1, v24
	v_cvt_pk_u8_f32 v25, v15, 1, v25
	v_cvt_pk_u8_f32 v22, v4, 2, v22
	v_cvt_pk_u8_f32 v23, v8, 2, v23
	v_cvt_pk_u8_f32 v24, v12, 2, v24
	v_cvt_pk_u8_f32 v25, v16, 2, v25
	v_cvt_pk_u8_f32 v22, v5, 3, v22
	v_cvt_pk_u8_f32 v23, v9, 3, v23
	v_cvt_pk_u8_f32 v24, v13, 3, v24
	v_cvt_pk_u8_f32 v25, v17, 3, v25
	global_store_dwordx4 v[0:1], v[22:25], off offset:1024 nt
	v_mul_f32_e32 v2, 0xbfb8aa3b, v130
	v_mul_f32_e32 v3, 0xbfb8aa3b, v131
	v_mul_f32_e32 v4, 0xbfb8aa3b, v132
	v_mul_f32_e32 v5, 0xbfb8aa3b, v133
	v_mul_f32_e32 v6, 0xbfb8aa3b, v126
	v_mul_f32_e32 v7, 0xbfb8aa3b, v127
	v_mul_f32_e32 v8, 0xbfb8aa3b, v128
	v_mul_f32_e32 v9, 0xbfb8aa3b, v129
	v_mul_f32_e32 v10, 0xbfb8aa3b, v122
	v_mul_f32_e32 v11, 0xbfb8aa3b, v123
	v_mul_f32_e32 v12, 0xbfb8aa3b, v124
	v_mul_f32_e32 v13, 0xbfb8aa3b, v125
	v_mul_f32_e32 v14, 0xbfb8aa3b, v118
	v_mul_f32_e32 v15, 0xbfb8aa3b, v119
	v_mul_f32_e32 v16, 0xbfb8aa3b, v120
	v_mul_f32_e32 v17, 0xbfb8aa3b, v121
	v_exp_f32_e32 v2, v2
	v_exp_f32_e32 v3, v3
	v_exp_f32_e32 v4, v4
	v_exp_f32_e32 v5, v5
	v_exp_f32_e32 v6, v6
	v_exp_f32_e32 v7, v7
	v_exp_f32_e32 v8, v8
	v_exp_f32_e32 v9, v9
	v_exp_f32_e32 v10, v10
	v_exp_f32_e32 v11, v11
	v_exp_f32_e32 v12, v12
	v_exp_f32_e32 v13, v13
	v_exp_f32_e32 v14, v14
	v_exp_f32_e32 v15, v15
	v_exp_f32_e32 v16, v16
	v_exp_f32_e32 v17, v17
	v_fma_f32 v2, v2, v217, v217 clamp
	v_fma_f32 v3, v3, v217, v217 clamp
	v_fma_f32 v4, v4, v217, v217 clamp
	v_fma_f32 v5, v5, v217, v217 clamp
	v_fma_f32 v6, v6, v217, v217 clamp
	v_fma_f32 v7, v7, v217, v217 clamp
	v_fma_f32 v8, v8, v217, v217 clamp
	v_fma_f32 v9, v9, v217, v217 clamp
	v_fma_f32 v10, v10, v217, v217 clamp
	v_fma_f32 v11, v11, v217, v217 clamp
	v_fma_f32 v12, v12, v217, v217 clamp
	v_fma_f32 v13, v13, v217, v217 clamp
	v_fma_f32 v14, v14, v217, v217 clamp
	v_fma_f32 v15, v15, v217, v217 clamp
	v_fma_f32 v16, v16, v217, v217 clamp
	v_fma_f32 v17, v17, v217, v217 clamp
	v_rcp_f32_e32 v2, v2
	v_rcp_f32_e32 v3, v3
	v_rcp_f32_e32 v4, v4
	v_rcp_f32_e32 v5, v5
	v_rcp_f32_e32 v6, v6
	v_rcp_f32_e32 v7, v7
	v_rcp_f32_e32 v8, v8
	v_rcp_f32_e32 v9, v9
	v_rcp_f32_e32 v10, v10
	v_rcp_f32_e32 v11, v11
	v_rcp_f32_e32 v12, v12
	v_rcp_f32_e32 v13, v13
	v_rcp_f32_e32 v14, v14
	v_rcp_f32_e32 v15, v15
	v_rcp_f32_e32 v16, v16
	v_rcp_f32_e32 v17, v17
	v_cvt_pk_u8_f32 v18, v2, 0, 0
	v_cvt_pk_u8_f32 v19, v6, 0, 0
	v_cvt_pk_u8_f32 v20, v10, 0, 0
	v_cvt_pk_u8_f32 v21, v14, 0, 0
	v_cvt_pk_u8_f32 v18, v3, 1, v18
	v_cvt_pk_u8_f32 v19, v7, 1, v19
	v_cvt_pk_u8_f32 v20, v11, 1, v20
	v_cvt_pk_u8_f32 v21, v15, 1, v21
	v_cvt_pk_u8_f32 v18, v4, 2, v18
	v_cvt_pk_u8_f32 v19, v8, 2, v19
	v_cvt_pk_u8_f32 v20, v12, 2, v20
	v_cvt_pk_u8_f32 v21, v16, 2, v21
	v_cvt_pk_u8_f32 v18, v5, 3, v18
	v_cvt_pk_u8_f32 v19, v9, 3, v19
	v_cvt_pk_u8_f32 v20, v13, 3, v20
	v_cvt_pk_u8_f32 v21, v17, 3, v21
	global_store_dwordx4 v[0:1], v[18:21], off offset:2048 nt
	v_mul_f32_e32 v2, 0xbfb8aa3b, v114
	v_mul_f32_e32 v3, 0xbfb8aa3b, v115
	v_mul_f32_e32 v4, 0xbfb8aa3b, v116
	v_mul_f32_e32 v5, 0xbfb8aa3b, v117
	v_mul_f32_e32 v6, 0xbfb8aa3b, v110
	v_mul_f32_e32 v7, 0xbfb8aa3b, v111
	v_mul_f32_e32 v8, 0xbfb8aa3b, v112
	v_mul_f32_e32 v9, 0xbfb8aa3b, v113
	v_mul_f32_e32 v10, 0xbfb8aa3b, v106
	v_mul_f32_e32 v11, 0xbfb8aa3b, v107
	v_mul_f32_e32 v12, 0xbfb8aa3b, v108
	v_mul_f32_e32 v13, 0xbfb8aa3b, v109
	v_mul_f32_e32 v14, 0xbfb8aa3b, v102
	v_mul_f32_e32 v15, 0xbfb8aa3b, v103
	v_mul_f32_e32 v16, 0xbfb8aa3b, v104
	v_mul_f32_e32 v17, 0xbfb8aa3b, v105
	v_exp_f32_e32 v2, v2
	v_exp_f32_e32 v3, v3
	v_exp_f32_e32 v4, v4
	v_exp_f32_e32 v5, v5
	v_exp_f32_e32 v6, v6
	v_exp_f32_e32 v7, v7
	v_exp_f32_e32 v8, v8
	v_exp_f32_e32 v9, v9
	v_exp_f32_e32 v10, v10
	v_exp_f32_e32 v11, v11
	v_exp_f32_e32 v12, v12
	v_exp_f32_e32 v13, v13
	v_exp_f32_e32 v14, v14
	v_exp_f32_e32 v15, v15
	v_exp_f32_e32 v16, v16
	v_exp_f32_e32 v17, v17
	v_fma_f32 v2, v2, v217, v217 clamp
	v_fma_f32 v3, v3, v217, v217 clamp
	v_fma_f32 v4, v4, v217, v217 clamp
	v_fma_f32 v5, v5, v217, v217 clamp
	v_fma_f32 v6, v6, v217, v217 clamp
	v_fma_f32 v7, v7, v217, v217 clamp
	v_fma_f32 v8, v8, v217, v217 clamp
	v_fma_f32 v9, v9, v217, v217 clamp
	v_fma_f32 v10, v10, v217, v217 clamp
	v_fma_f32 v11, v11, v217, v217 clamp
	v_fma_f32 v12, v12, v217, v217 clamp
	v_fma_f32 v13, v13, v217, v217 clamp
	v_fma_f32 v14, v14, v217, v217 clamp
	v_fma_f32 v15, v15, v217, v217 clamp
	v_fma_f32 v16, v16, v217, v217 clamp
	v_fma_f32 v17, v17, v217, v217 clamp
	v_rcp_f32_e32 v2, v2
	v_rcp_f32_e32 v3, v3
	v_rcp_f32_e32 v4, v4
	v_rcp_f32_e32 v5, v5
	v_rcp_f32_e32 v6, v6
	v_rcp_f32_e32 v7, v7
	v_rcp_f32_e32 v8, v8
	v_rcp_f32_e32 v9, v9
	v_rcp_f32_e32 v10, v10
	v_rcp_f32_e32 v11, v11
	v_rcp_f32_e32 v12, v12
	v_rcp_f32_e32 v13, v13
	v_rcp_f32_e32 v14, v14
	v_rcp_f32_e32 v15, v15
	v_rcp_f32_e32 v16, v16
	v_rcp_f32_e32 v17, v17
	v_cvt_pk_u8_f32 v22, v2, 0, 0
	v_cvt_pk_u8_f32 v23, v6, 0, 0
	v_cvt_pk_u8_f32 v24, v10, 0, 0
	v_cvt_pk_u8_f32 v25, v14, 0, 0
	v_cvt_pk_u8_f32 v22, v3, 1, v22
	v_cvt_pk_u8_f32 v23, v7, 1, v23
	v_cvt_pk_u8_f32 v24, v11, 1, v24
	v_cvt_pk_u8_f32 v25, v15, 1, v25
	v_cvt_pk_u8_f32 v22, v4, 2, v22
	v_cvt_pk_u8_f32 v23, v8, 2, v23
	v_cvt_pk_u8_f32 v24, v12, 2, v24
	v_cvt_pk_u8_f32 v25, v16, 2, v25
	v_cvt_pk_u8_f32 v22, v5, 3, v22
	v_cvt_pk_u8_f32 v23, v9, 3, v23
	v_cvt_pk_u8_f32 v24, v13, 3, v24
	v_cvt_pk_u8_f32 v25, v17, 3, v25
	global_store_dwordx4 v[0:1], v[22:25], off offset:3072 nt
	v_mul_f32_e32 v2, 0xbfb8aa3b, v98
	v_mul_f32_e32 v3, 0xbfb8aa3b, v99
	v_mul_f32_e32 v4, 0xbfb8aa3b, v100
	v_mul_f32_e32 v5, 0xbfb8aa3b, v101
	v_mul_f32_e32 v6, 0xbfb8aa3b, v94
	v_mul_f32_e32 v7, 0xbfb8aa3b, v95
	v_mul_f32_e32 v8, 0xbfb8aa3b, v96
	v_mul_f32_e32 v9, 0xbfb8aa3b, v97
	v_mul_f32_e32 v10, 0xbfb8aa3b, v90
	v_mul_f32_e32 v11, 0xbfb8aa3b, v91
	v_mul_f32_e32 v12, 0xbfb8aa3b, v92
	v_mul_f32_e32 v13, 0xbfb8aa3b, v93
	v_mul_f32_e32 v14, 0xbfb8aa3b, v86
	v_mul_f32_e32 v15, 0xbfb8aa3b, v87
	v_mul_f32_e32 v16, 0xbfb8aa3b, v88
	v_mul_f32_e32 v17, 0xbfb8aa3b, v89
	v_exp_f32_e32 v2, v2
	v_exp_f32_e32 v3, v3
	v_exp_f32_e32 v4, v4
	v_exp_f32_e32 v5, v5
	v_exp_f32_e32 v6, v6
	v_exp_f32_e32 v7, v7
	v_exp_f32_e32 v8, v8
	v_exp_f32_e32 v9, v9
	v_exp_f32_e32 v10, v10
	v_exp_f32_e32 v11, v11
	v_exp_f32_e32 v12, v12
	v_exp_f32_e32 v13, v13
	v_exp_f32_e32 v14, v14
	v_exp_f32_e32 v15, v15
	v_exp_f32_e32 v16, v16
	v_exp_f32_e32 v17, v17
	v_fma_f32 v2, v2, v217, v217 clamp
	v_fma_f32 v3, v3, v217, v217 clamp
	v_fma_f32 v4, v4, v217, v217 clamp
	v_fma_f32 v5, v5, v217, v217 clamp
	v_fma_f32 v6, v6, v217, v217 clamp
	v_fma_f32 v7, v7, v217, v217 clamp
	v_fma_f32 v8, v8, v217, v217 clamp
	v_fma_f32 v9, v9, v217, v217 clamp
	v_fma_f32 v10, v10, v217, v217 clamp
	v_fma_f32 v11, v11, v217, v217 clamp
	v_fma_f32 v12, v12, v217, v217 clamp
	v_fma_f32 v13, v13, v217, v217 clamp
	v_fma_f32 v14, v14, v217, v217 clamp
	v_fma_f32 v15, v15, v217, v217 clamp
	v_fma_f32 v16, v16, v217, v217 clamp
	v_fma_f32 v17, v17, v217, v217 clamp
	v_rcp_f32_e32 v2, v2
	v_rcp_f32_e32 v3, v3
	v_rcp_f32_e32 v4, v4
	v_rcp_f32_e32 v5, v5
	v_rcp_f32_e32 v6, v6
	v_rcp_f32_e32 v7, v7
	v_rcp_f32_e32 v8, v8
	v_rcp_f32_e32 v9, v9
	v_rcp_f32_e32 v10, v10
	v_rcp_f32_e32 v11, v11
	v_rcp_f32_e32 v12, v12
	v_rcp_f32_e32 v13, v13
	v_rcp_f32_e32 v14, v14
	v_rcp_f32_e32 v15, v15
	v_rcp_f32_e32 v16, v16
	v_rcp_f32_e32 v17, v17
	v_cvt_pk_u8_f32 v18, v2, 0, 0
	v_cvt_pk_u8_f32 v19, v6, 0, 0
	v_cvt_pk_u8_f32 v20, v10, 0, 0
	v_cvt_pk_u8_f32 v21, v14, 0, 0
	v_cvt_pk_u8_f32 v18, v3, 1, v18
	v_cvt_pk_u8_f32 v19, v7, 1, v19
	v_cvt_pk_u8_f32 v20, v11, 1, v20
	v_cvt_pk_u8_f32 v21, v15, 1, v21
	v_cvt_pk_u8_f32 v18, v4, 2, v18
	v_cvt_pk_u8_f32 v19, v8, 2, v19
	v_cvt_pk_u8_f32 v20, v12, 2, v20
	v_cvt_pk_u8_f32 v21, v16, 2, v21
	v_cvt_pk_u8_f32 v18, v5, 3, v18
	v_cvt_pk_u8_f32 v19, v9, 3, v19
	v_cvt_pk_u8_f32 v20, v13, 3, v20
	v_cvt_pk_u8_f32 v21, v17, 3, v21
	global_store_dwordx4 v[26:27], v[18:21], off nt
	v_mul_f32_e32 v2, 0xbfb8aa3b, v82
	v_mul_f32_e32 v3, 0xbfb8aa3b, v83
	v_mul_f32_e32 v4, 0xbfb8aa3b, v84
	v_mul_f32_e32 v5, 0xbfb8aa3b, v85
	v_mul_f32_e32 v6, 0xbfb8aa3b, v78
	v_mul_f32_e32 v7, 0xbfb8aa3b, v79
	v_mul_f32_e32 v8, 0xbfb8aa3b, v80
	v_mul_f32_e32 v9, 0xbfb8aa3b, v81
	v_mul_f32_e32 v10, 0xbfb8aa3b, v74
	v_mul_f32_e32 v11, 0xbfb8aa3b, v75
	v_mul_f32_e32 v12, 0xbfb8aa3b, v76
	v_mul_f32_e32 v13, 0xbfb8aa3b, v77
	v_mul_f32_e32 v14, 0xbfb8aa3b, v70
	v_mul_f32_e32 v15, 0xbfb8aa3b, v71
	v_mul_f32_e32 v16, 0xbfb8aa3b, v72
	v_mul_f32_e32 v17, 0xbfb8aa3b, v73
	v_exp_f32_e32 v2, v2
	v_exp_f32_e32 v3, v3
	v_exp_f32_e32 v4, v4
	v_exp_f32_e32 v5, v5
	v_exp_f32_e32 v6, v6
	v_exp_f32_e32 v7, v7
	v_exp_f32_e32 v8, v8
	v_exp_f32_e32 v9, v9
	v_exp_f32_e32 v10, v10
	v_exp_f32_e32 v11, v11
	v_exp_f32_e32 v12, v12
	v_exp_f32_e32 v13, v13
	v_exp_f32_e32 v14, v14
	v_exp_f32_e32 v15, v15
	v_exp_f32_e32 v16, v16
	v_exp_f32_e32 v17, v17
	v_fma_f32 v2, v2, v217, v217 clamp
	v_fma_f32 v3, v3, v217, v217 clamp
	v_fma_f32 v4, v4, v217, v217 clamp
	v_fma_f32 v5, v5, v217, v217 clamp
	v_fma_f32 v6, v6, v217, v217 clamp
	v_fma_f32 v7, v7, v217, v217 clamp
	v_fma_f32 v8, v8, v217, v217 clamp
	v_fma_f32 v9, v9, v217, v217 clamp
	v_fma_f32 v10, v10, v217, v217 clamp
	v_fma_f32 v11, v11, v217, v217 clamp
	v_fma_f32 v12, v12, v217, v217 clamp
	v_fma_f32 v13, v13, v217, v217 clamp
	v_fma_f32 v14, v14, v217, v217 clamp
	v_fma_f32 v15, v15, v217, v217 clamp
	v_fma_f32 v16, v16, v217, v217 clamp
	v_fma_f32 v17, v17, v217, v217 clamp
	v_rcp_f32_e32 v2, v2
	v_rcp_f32_e32 v3, v3
	v_rcp_f32_e32 v4, v4
	v_rcp_f32_e32 v5, v5
	v_rcp_f32_e32 v6, v6
	v_rcp_f32_e32 v7, v7
	v_rcp_f32_e32 v8, v8
	v_rcp_f32_e32 v9, v9
	v_rcp_f32_e32 v10, v10
	v_rcp_f32_e32 v11, v11
	v_rcp_f32_e32 v12, v12
	v_rcp_f32_e32 v13, v13
	v_rcp_f32_e32 v14, v14
	v_rcp_f32_e32 v15, v15
	v_rcp_f32_e32 v16, v16
	v_rcp_f32_e32 v17, v17
	v_cvt_pk_u8_f32 v22, v2, 0, 0
	v_cvt_pk_u8_f32 v23, v6, 0, 0
	v_cvt_pk_u8_f32 v24, v10, 0, 0
	v_cvt_pk_u8_f32 v25, v14, 0, 0
	v_cvt_pk_u8_f32 v22, v3, 1, v22
	v_cvt_pk_u8_f32 v23, v7, 1, v23
	v_cvt_pk_u8_f32 v24, v11, 1, v24
	v_cvt_pk_u8_f32 v25, v15, 1, v25
	v_cvt_pk_u8_f32 v22, v4, 2, v22
	v_cvt_pk_u8_f32 v23, v8, 2, v23
	v_cvt_pk_u8_f32 v24, v12, 2, v24
	v_cvt_pk_u8_f32 v25, v16, 2, v25
	v_cvt_pk_u8_f32 v22, v5, 3, v22
	v_cvt_pk_u8_f32 v23, v9, 3, v23
	v_cvt_pk_u8_f32 v24, v13, 3, v24
	v_cvt_pk_u8_f32 v25, v17, 3, v25
	global_store_dwordx4 v[26:27], v[22:25], off offset:1024 nt
	v_mul_f32_e32 v2, 0xbfb8aa3b, v66
	v_mul_f32_e32 v3, 0xbfb8aa3b, v67
	v_mul_f32_e32 v4, 0xbfb8aa3b, v68
	v_mul_f32_e32 v5, 0xbfb8aa3b, v69
	v_mul_f32_e32 v6, 0xbfb8aa3b, v62
	v_mul_f32_e32 v7, 0xbfb8aa3b, v63
	v_mul_f32_e32 v8, 0xbfb8aa3b, v64
	v_mul_f32_e32 v9, 0xbfb8aa3b, v65
	v_mul_f32_e32 v10, 0xbfb8aa3b, v58
	v_mul_f32_e32 v11, 0xbfb8aa3b, v59
	v_mul_f32_e32 v12, 0xbfb8aa3b, v60
	v_mul_f32_e32 v13, 0xbfb8aa3b, v61
	v_mul_f32_e32 v14, 0xbfb8aa3b, v54
	v_mul_f32_e32 v15, 0xbfb8aa3b, v55
	v_mul_f32_e32 v16, 0xbfb8aa3b, v56
	v_mul_f32_e32 v17, 0xbfb8aa3b, v57
	v_exp_f32_e32 v2, v2
	v_exp_f32_e32 v3, v3
	v_exp_f32_e32 v4, v4
	v_exp_f32_e32 v5, v5
	v_exp_f32_e32 v6, v6
	v_exp_f32_e32 v7, v7
	v_exp_f32_e32 v8, v8
	v_exp_f32_e32 v9, v9
	v_exp_f32_e32 v10, v10
	v_exp_f32_e32 v11, v11
	v_exp_f32_e32 v12, v12
	v_exp_f32_e32 v13, v13
	v_exp_f32_e32 v14, v14
	v_exp_f32_e32 v15, v15
	v_exp_f32_e32 v16, v16
	v_exp_f32_e32 v17, v17
	v_fma_f32 v2, v2, v217, v217 clamp
	v_fma_f32 v3, v3, v217, v217 clamp
	v_fma_f32 v4, v4, v217, v217 clamp
	v_fma_f32 v5, v5, v217, v217 clamp
	v_fma_f32 v6, v6, v217, v217 clamp
	v_fma_f32 v7, v7, v217, v217 clamp
	v_fma_f32 v8, v8, v217, v217 clamp
	v_fma_f32 v9, v9, v217, v217 clamp
	v_fma_f32 v10, v10, v217, v217 clamp
	v_fma_f32 v11, v11, v217, v217 clamp
	v_fma_f32 v12, v12, v217, v217 clamp
	v_fma_f32 v13, v13, v217, v217 clamp
	v_fma_f32 v14, v14, v217, v217 clamp
	v_fma_f32 v15, v15, v217, v217 clamp
	v_fma_f32 v16, v16, v217, v217 clamp
	v_fma_f32 v17, v17, v217, v217 clamp
	v_rcp_f32_e32 v2, v2
	v_rcp_f32_e32 v3, v3
	v_rcp_f32_e32 v4, v4
	v_rcp_f32_e32 v5, v5
	v_rcp_f32_e32 v6, v6
	v_rcp_f32_e32 v7, v7
	v_rcp_f32_e32 v8, v8
	v_rcp_f32_e32 v9, v9
	v_rcp_f32_e32 v10, v10
	v_rcp_f32_e32 v11, v11
	v_rcp_f32_e32 v12, v12
	v_rcp_f32_e32 v13, v13
	v_rcp_f32_e32 v14, v14
	v_rcp_f32_e32 v15, v15
	v_rcp_f32_e32 v16, v16
	v_rcp_f32_e32 v17, v17
	v_cvt_pk_u8_f32 v18, v2, 0, 0
	v_cvt_pk_u8_f32 v19, v6, 0, 0
	v_cvt_pk_u8_f32 v20, v10, 0, 0
	v_cvt_pk_u8_f32 v21, v14, 0, 0
	v_cvt_pk_u8_f32 v18, v3, 1, v18
	v_cvt_pk_u8_f32 v19, v7, 1, v19
	v_cvt_pk_u8_f32 v20, v11, 1, v20
	v_cvt_pk_u8_f32 v21, v15, 1, v21
	v_cvt_pk_u8_f32 v18, v4, 2, v18
	v_cvt_pk_u8_f32 v19, v8, 2, v19
	v_cvt_pk_u8_f32 v20, v12, 2, v20
	v_cvt_pk_u8_f32 v21, v16, 2, v21
	v_cvt_pk_u8_f32 v18, v5, 3, v18
	v_cvt_pk_u8_f32 v19, v9, 3, v19
	v_cvt_pk_u8_f32 v20, v13, 3, v20
	v_cvt_pk_u8_f32 v21, v17, 3, v21
	global_store_dwordx4 v[26:27], v[18:21], off offset:2048 nt
	v_mul_f32_e32 v2, 0xbfb8aa3b, v50
	v_mul_f32_e32 v3, 0xbfb8aa3b, v51
	v_mul_f32_e32 v4, 0xbfb8aa3b, v52
	v_mul_f32_e32 v5, 0xbfb8aa3b, v53
	v_mul_f32_e32 v6, 0xbfb8aa3b, v46
	v_mul_f32_e32 v7, 0xbfb8aa3b, v47
	v_mul_f32_e32 v8, 0xbfb8aa3b, v48
	v_mul_f32_e32 v9, 0xbfb8aa3b, v49
	v_mul_f32_e32 v10, 0xbfb8aa3b, v42
	v_mul_f32_e32 v11, 0xbfb8aa3b, v43
	v_mul_f32_e32 v12, 0xbfb8aa3b, v44
	v_mul_f32_e32 v13, 0xbfb8aa3b, v45
	v_mul_f32_e32 v14, 0xbfb8aa3b, v38
	v_mul_f32_e32 v15, 0xbfb8aa3b, v39
	v_mul_f32_e32 v16, 0xbfb8aa3b, v40
	v_mul_f32_e32 v17, 0xbfb8aa3b, v41
	v_exp_f32_e32 v2, v2
	v_exp_f32_e32 v3, v3
	v_exp_f32_e32 v4, v4
	v_exp_f32_e32 v5, v5
	v_exp_f32_e32 v6, v6
	v_exp_f32_e32 v7, v7
	v_exp_f32_e32 v8, v8
	v_exp_f32_e32 v9, v9
	v_exp_f32_e32 v10, v10
	v_exp_f32_e32 v11, v11
	v_exp_f32_e32 v12, v12
	v_exp_f32_e32 v13, v13
	v_exp_f32_e32 v14, v14
	v_exp_f32_e32 v15, v15
	v_exp_f32_e32 v16, v16
	v_exp_f32_e32 v17, v17
	v_fma_f32 v2, v2, v217, v217 clamp
	v_fma_f32 v3, v3, v217, v217 clamp
	v_fma_f32 v4, v4, v217, v217 clamp
	v_fma_f32 v5, v5, v217, v217 clamp
	v_fma_f32 v6, v6, v217, v217 clamp
	v_fma_f32 v7, v7, v217, v217 clamp
	v_fma_f32 v8, v8, v217, v217 clamp
	v_fma_f32 v9, v9, v217, v217 clamp
	v_fma_f32 v10, v10, v217, v217 clamp
	v_fma_f32 v11, v11, v217, v217 clamp
	v_fma_f32 v12, v12, v217, v217 clamp
	v_fma_f32 v13, v13, v217, v217 clamp
	v_fma_f32 v14, v14, v217, v217 clamp
	v_fma_f32 v15, v15, v217, v217 clamp
	v_fma_f32 v16, v16, v217, v217 clamp
	v_fma_f32 v17, v17, v217, v217 clamp
	v_rcp_f32_e32 v2, v2
	v_rcp_f32_e32 v3, v3
	v_rcp_f32_e32 v4, v4
	v_rcp_f32_e32 v5, v5
	v_rcp_f32_e32 v6, v6
	v_rcp_f32_e32 v7, v7
	v_rcp_f32_e32 v8, v8
	v_rcp_f32_e32 v9, v9
	v_rcp_f32_e32 v10, v10
	v_rcp_f32_e32 v11, v11
	v_rcp_f32_e32 v12, v12
	v_rcp_f32_e32 v13, v13
	v_rcp_f32_e32 v14, v14
	v_rcp_f32_e32 v15, v15
	v_rcp_f32_e32 v16, v16
	v_rcp_f32_e32 v17, v17
	v_cvt_pk_u8_f32 v22, v2, 0, 0
	v_cvt_pk_u8_f32 v23, v6, 0, 0
	v_cvt_pk_u8_f32 v24, v10, 0, 0
	v_cvt_pk_u8_f32 v25, v14, 0, 0
	v_cvt_pk_u8_f32 v22, v3, 1, v22
	v_cvt_pk_u8_f32 v23, v7, 1, v23
	v_cvt_pk_u8_f32 v24, v11, 1, v24
	v_cvt_pk_u8_f32 v25, v15, 1, v25
	v_cvt_pk_u8_f32 v22, v4, 2, v22
	v_cvt_pk_u8_f32 v23, v8, 2, v23
	v_cvt_pk_u8_f32 v24, v12, 2, v24
	v_cvt_pk_u8_f32 v25, v16, 2, v25
	v_cvt_pk_u8_f32 v22, v5, 3, v22
	v_cvt_pk_u8_f32 v23, v9, 3, v23
	v_cvt_pk_u8_f32 v24, v13, 3, v24
	v_cvt_pk_u8_f32 v25, v17, 3, v25
	global_store_dwordx4 v[26:27], v[22:25], off offset:3072 nt
	s_andn2_b64 vcc, exec, s[64:65]
	s_mov_b64 s[8:9], -1
	s_cbranch_vccnz .LBB0_310
	s_branch .LBB0_367

.LBB0_348:
	s_cmp_lt_i32 s87, 3
	s_cbranch_scc1 .Lpxa_gen_a
	s_add_i32 s0, s87, -9
	s_cmp_lt_u32 s0, 2
	s_cbranch_scc1 .Lpxa_gen_a
	s_lshl_b32 s0, s88, 8
	s_add_i32 s0, s0, s42
	v_or_b32_e32 v202, s0, v204
	s_lshl_b32 s10, s87, 8
	s_mov_b32 s11, 0
	v_lshl_add_u64 v[198:199], s[10:11], 1, v[188:189]
	v_mov_b32_e32 v203, 0
	v_lshlrev_b64 v[18:19], 13, v[202:203]
	v_lshl_add_u64 v[22:23], v[198:199], 0, v[18:19]
	v_cvt_pk_bf16_f32 v0, v162, v163
	v_cvt_pk_bf16_f32 v1, v164, v165
	v_cvt_pk_bf16_f32 v2, v158, v159
	v_cvt_pk_bf16_f32 v3, v160, v161
	global_store_dwordx4 v[22:23], v[0:3], off
	v_cvt_pk_bf16_f32 v4, v154, v155
	v_cvt_pk_bf16_f32 v5, v156, v157
	v_cvt_pk_bf16_f32 v6, v150, v151
	v_cvt_pk_bf16_f32 v7, v152, v153
	global_store_dwordx4 v[22:23], v[4:7], off offset:256
	s_mov_b32 s8, 0x20000
	s_mov_b32 s9, 0
	v_lshl_add_u64 v[26:27], v[22:23], 0, s[8:9]
	v_cvt_pk_bf16_f32 v8, v146, v147
	v_cvt_pk_bf16_f32 v9, v148, v149
	v_cvt_pk_bf16_f32 v10, v142, v143
	v_cvt_pk_bf16_f32 v11, v144, v145
	global_store_dwordx4 v[26:27], v[8:11], off
	v_cvt_pk_bf16_f32 v12, v138, v139
	v_cvt_pk_bf16_f32 v13, v140, v141
	v_cvt_pk_bf16_f32 v14, v134, v135
	v_cvt_pk_bf16_f32 v15, v136, v137
	global_store_dwordx4 v[26:27], v[12:15], off offset:256
	s_mov_b32 s8, 0x40000
	s_mov_b32 s9, 0
	v_lshl_add_u64 v[28:29], v[22:23], 0, s[8:9]
	v_cvt_pk_bf16_f32 v0, v130, v131
	v_cvt_pk_bf16_f32 v1, v132, v133
	v_cvt_pk_bf16_f32 v2, v126, v127
	v_cvt_pk_bf16_f32 v3, v128, v129
	global_store_dwordx4 v[28:29], v[0:3], off
	v_cvt_pk_bf16_f32 v4, v122, v123
	v_cvt_pk_bf16_f32 v5, v124, v125
	v_cvt_pk_bf16_f32 v6, v118, v119
	v_cvt_pk_bf16_f32 v7, v120, v121
	global_store_dwordx4 v[28:29], v[4:7], off offset:256
	s_mov_b32 s8, 0x60000
	s_mov_b32 s9, 0
	v_lshl_add_u64 v[24:25], v[22:23], 0, s[8:9]
	v_cvt_pk_bf16_f32 v8, v114, v115
	v_cvt_pk_bf16_f32 v9, v116, v117
	v_cvt_pk_bf16_f32 v10, v110, v111
	v_cvt_pk_bf16_f32 v11, v112, v113
	global_store_dwordx4 v[24:25], v[8:11], off
	v_cvt_pk_bf16_f32 v12, v106, v107
	v_cvt_pk_bf16_f32 v13, v108, v109
	v_cvt_pk_bf16_f32 v14, v102, v103
	v_cvt_pk_bf16_f32 v15, v104, v105
	global_store_dwordx4 v[24:25], v[12:15], off offset:256
	s_mov_b32 s8, 0x100000
	s_mov_b32 s9, 0
	v_lshl_add_u64 v[26:27], v[22:23], 0, s[8:9]
	v_cvt_pk_bf16_f32 v0, v98, v99
	v_cvt_pk_bf16_f32 v1, v100, v101
	v_cvt_pk_bf16_f32 v2, v94, v95
	v_cvt_pk_bf16_f32 v3, v96, v97
	global_store_dwordx4 v[26:27], v[0:3], off
	v_cvt_pk_bf16_f32 v4, v90, v91
	v_cvt_pk_bf16_f32 v5, v92, v93
	v_cvt_pk_bf16_f32 v6, v86, v87
	v_cvt_pk_bf16_f32 v7, v88, v89
	global_store_dwordx4 v[26:27], v[4:7], off offset:256
	s_mov_b32 s8, 0x120000
	s_mov_b32 s9, 0
	v_lshl_add_u64 v[28:29], v[22:23], 0, s[8:9]
	v_cvt_pk_bf16_f32 v8, v82, v83
	v_cvt_pk_bf16_f32 v9, v84, v85
	v_cvt_pk_bf16_f32 v10, v78, v79
	v_cvt_pk_bf16_f32 v11, v80, v81
	global_store_dwordx4 v[28:29], v[8:11], off
	v_cvt_pk_bf16_f32 v12, v74, v75
	v_cvt_pk_bf16_f32 v13, v76, v77
	v_cvt_pk_bf16_f32 v14, v70, v71
	v_cvt_pk_bf16_f32 v15, v72, v73
	global_store_dwordx4 v[28:29], v[12:15], off offset:256
	s_mov_b32 s8, 0x140000
	s_mov_b32 s9, 0
	v_lshl_add_u64 v[24:25], v[22:23], 0, s[8:9]
	v_cvt_pk_bf16_f32 v0, v66, v67
	v_cvt_pk_bf16_f32 v1, v68, v69
	v_cvt_pk_bf16_f32 v2, v62, v63
	v_cvt_pk_bf16_f32 v3, v64, v65
	global_store_dwordx4 v[24:25], v[0:3], off
	v_cvt_pk_bf16_f32 v4, v58, v59
	v_cvt_pk_bf16_f32 v5, v60, v61
	v_cvt_pk_bf16_f32 v6, v54, v55
	v_cvt_pk_bf16_f32 v7, v56, v57
	global_store_dwordx4 v[24:25], v[4:7], off offset:256
	s_mov_b32 s8, 0x160000
	s_mov_b32 s9, 0
	v_lshl_add_u64 v[26:27], v[22:23], 0, s[8:9]
	v_cvt_pk_bf16_f32 v8, v50, v51
	v_cvt_pk_bf16_f32 v9, v52, v53
	v_cvt_pk_bf16_f32 v10, v46, v47
	v_cvt_pk_bf16_f32 v11, v48, v49
	global_store_dwordx4 v[26:27], v[8:11], off
	v_cvt_pk_bf16_f32 v12, v42, v43
	v_cvt_pk_bf16_f32 v13, v44, v45
	v_cvt_pk_bf16_f32 v14, v38, v39
	v_cvt_pk_bf16_f32 v15, v40, v41
	global_store_dwordx4 v[26:27], v[12:15], off offset:256
	s_branch .LBB0_366

.LBB0_517:
	s_and_b64 vcc, exec, s[8:9]
	s_cbranch_vccz .LBB0_538
	s_lshl_b32 s9, s72, 2
	s_add_i32 s0, s72, -16
	s_lshl_b32 s8, s73, 4
	s_and_b32 s9, s9, 12
	s_or_b32 s8, s9, s8
	s_lshr_b32 s0, s0, 2
	s_add_i32 s8, s8, s0
	s_ashr_i32 s9, s8, 31
	s_lshl_b64 s[8:9], s[8:9], 16
	v_lshl_add_u64 v[0:1], v[190:191], 0, s[8:9]
	s_mov_b64 s[8:9], 0x1000
	v_lshl_add_u64 v[26:27], v[0:1], 0, s[8:9]
	v_mul_f32_e32 v2, 0xbfb8aa3b, v162
	v_mul_f32_e32 v3, 0xbfb8aa3b, v163
	v_mul_f32_e32 v4, 0xbfb8aa3b, v164
	v_mul_f32_e32 v5, 0xbfb8aa3b, v165
	v_mul_f32_e32 v6, 0xbfb8aa3b, v158
	v_mul_f32_e32 v7, 0xbfb8aa3b, v159
	v_mul_f32_e32 v8, 0xbfb8aa3b, v160
	v_mul_f32_e32 v9, 0xbfb8aa3b, v161
	v_mul_f32_e32 v10, 0xbfb8aa3b, v154
	v_mul_f32_e32 v11, 0xbfb8aa3b, v155
	v_mul_f32_e32 v12, 0xbfb8aa3b, v156
	v_mul_f32_e32 v13, 0xbfb8aa3b, v157
	v_mul_f32_e32 v14, 0xbfb8aa3b, v150
	v_mul_f32_e32 v15, 0xbfb8aa3b, v151
	v_mul_f32_e32 v16, 0xbfb8aa3b, v152
	v_mul_f32_e32 v17, 0xbfb8aa3b, v153
	v_exp_f32_e32 v2, v2
	v_exp_f32_e32 v3, v3
	v_exp_f32_e32 v4, v4
	v_exp_f32_e32 v5, v5
	v_exp_f32_e32 v6, v6
	v_exp_f32_e32 v7, v7
	v_exp_f32_e32 v8, v8
	v_exp_f32_e32 v9, v9
	v_exp_f32_e32 v10, v10
	v_exp_f32_e32 v11, v11
	v_exp_f32_e32 v12, v12
	v_exp_f32_e32 v13, v13
	v_exp_f32_e32 v14, v14
	v_exp_f32_e32 v15, v15
	v_exp_f32_e32 v16, v16
	v_exp_f32_e32 v17, v17
	v_fma_f32 v2, v2, v217, v217 clamp
	v_fma_f32 v3, v3, v217, v217 clamp
	v_fma_f32 v4, v4, v217, v217 clamp
	v_fma_f32 v5, v5, v217, v217 clamp
	v_fma_f32 v6, v6, v217, v217 clamp
	v_fma_f32 v7, v7, v217, v217 clamp
	v_fma_f32 v8, v8, v217, v217 clamp
	v_fma_f32 v9, v9, v217, v217 clamp
	v_fma_f32 v10, v10, v217, v217 clamp
	v_fma_f32 v11, v11, v217, v217 clamp
	v_fma_f32 v12, v12, v217, v217 clamp
	v_fma_f32 v13, v13, v217, v217 clamp
	v_fma_f32 v14, v14, v217, v217 clamp
	v_fma_f32 v15, v15, v217, v217 clamp
	v_fma_f32 v16, v16, v217, v217 clamp
	v_fma_f32 v17, v17, v217, v217 clamp
	v_rcp_f32_e32 v2, v2
	v_rcp_f32_e32 v3, v3
	v_rcp_f32_e32 v4, v4
	v_rcp_f32_e32 v5, v5
	v_rcp_f32_e32 v6, v6
	v_rcp_f32_e32 v7, v7
	v_rcp_f32_e32 v8, v8
	v_rcp_f32_e32 v9, v9
	v_rcp_f32_e32 v10, v10
	v_rcp_f32_e32 v11, v11
	v_rcp_f32_e32 v12, v12
	v_rcp_f32_e32 v13, v13
	v_rcp_f32_e32 v14, v14
	v_rcp_f32_e32 v15, v15
	v_rcp_f32_e32 v16, v16
	v_rcp_f32_e32 v17, v17
	v_cvt_pk_u8_f32 v18, v2, 0, 0
	v_cvt_pk_u8_f32 v19, v6, 0, 0
	v_cvt_pk_u8_f32 v20, v10, 0, 0
	v_cvt_pk_u8_f32 v21, v14, 0, 0
	v_cvt_pk_u8_f32 v18, v3, 1, v18
	v_cvt_pk_u8_f32 v19, v7, 1, v19
	v_cvt_pk_u8_f32 v20, v11, 1, v20
	v_cvt_pk_u8_f32 v21, v15, 1, v21
	v_cvt_pk_u8_f32 v18, v4, 2, v18
	v_cvt_pk_u8_f32 v19, v8, 2, v19
	v_cvt_pk_u8_f32 v20, v12, 2, v20
	v_cvt_pk_u8_f32 v21, v16, 2, v21
	v_cvt_pk_u8_f32 v18, v5, 3, v18
	v_cvt_pk_u8_f32 v19, v9, 3, v19
	v_cvt_pk_u8_f32 v20, v13, 3, v20
	v_cvt_pk_u8_f32 v21, v17, 3, v21
	global_store_dwordx4 v[0:1], v[18:21], off nt
	v_mul_f32_e32 v2, 0xbfb8aa3b, v146
	v_mul_f32_e32 v3, 0xbfb8aa3b, v147
	v_mul_f32_e32 v4, 0xbfb8aa3b, v148
	v_mul_f32_e32 v5, 0xbfb8aa3b, v149
	v_mul_f32_e32 v6, 0xbfb8aa3b, v142
	v_mul_f32_e32 v7, 0xbfb8aa3b, v143
	v_mul_f32_e32 v8, 0xbfb8aa3b, v144
	v_mul_f32_e32 v9, 0xbfb8aa3b, v145
	v_mul_f32_e32 v10, 0xbfb8aa3b, v138
	v_mul_f32_e32 v11, 0xbfb8aa3b, v139
	v_mul_f32_e32 v12, 0xbfb8aa3b, v140
	v_mul_f32_e32 v13, 0xbfb8aa3b, v141
	v_mul_f32_e32 v14, 0xbfb8aa3b, v134
	v_mul_f32_e32 v15, 0xbfb8aa3b, v135
	v_mul_f32_e32 v16, 0xbfb8aa3b, v136
	v_mul_f32_e32 v17, 0xbfb8aa3b, v137
	v_exp_f32_e32 v2, v2
	v_exp_f32_e32 v3, v3
	v_exp_f32_e32 v4, v4
	v_exp_f32_e32 v5, v5
	v_exp_f32_e32 v6, v6
	v_exp_f32_e32 v7, v7
	v_exp_f32_e32 v8, v8
	v_exp_f32_e32 v9, v9
	v_exp_f32_e32 v10, v10
	v_exp_f32_e32 v11, v11
	v_exp_f32_e32 v12, v12
	v_exp_f32_e32 v13, v13
	v_exp_f32_e32 v14, v14
	v_exp_f32_e32 v15, v15
	v_exp_f32_e32 v16, v16
	v_exp_f32_e32 v17, v17
	v_fma_f32 v2, v2, v217, v217 clamp
	v_fma_f32 v3, v3, v217, v217 clamp
	v_fma_f32 v4, v4, v217, v217 clamp
	v_fma_f32 v5, v5, v217, v217 clamp
	v_fma_f32 v6, v6, v217, v217 clamp
	v_fma_f32 v7, v7, v217, v217 clamp
	v_fma_f32 v8, v8, v217, v217 clamp
	v_fma_f32 v9, v9, v217, v217 clamp
	v_fma_f32 v10, v10, v217, v217 clamp
	v_fma_f32 v11, v11, v217, v217 clamp
	v_fma_f32 v12, v12, v217, v217 clamp
	v_fma_f32 v13, v13, v217, v217 clamp
	v_fma_f32 v14, v14, v217, v217 clamp
	v_fma_f32 v15, v15, v217, v217 clamp
	v_fma_f32 v16, v16, v217, v217 clamp
	v_fma_f32 v17, v17, v217, v217 clamp
	v_rcp_f32_e32 v2, v2
	v_rcp_f32_e32 v3, v3
	v_rcp_f32_e32 v4, v4
	v_rcp_f32_e32 v5, v5
	v_rcp_f32_e32 v6, v6
	v_rcp_f32_e32 v7, v7
	v_rcp_f32_e32 v8, v8
	v_rcp_f32_e32 v9, v9
	v_rcp_f32_e32 v10, v10
	v_rcp_f32_e32 v11, v11
	v_rcp_f32_e32 v12, v12
	v_rcp_f32_e32 v13, v13
	v_rcp_f32_e32 v14, v14
	v_rcp_f32_e32 v15, v15
	v_rcp_f32_e32 v16, v16
	v_rcp_f32_e32 v17, v17
	v_cvt_pk_u8_f32 v22, v2, 0, 0
	v_cvt_pk_u8_f32 v23, v6, 0, 0
	v_cvt_pk_u8_f32 v24, v10, 0, 0
	v_cvt_pk_u8_f32 v25, v14, 0, 0
	v_cvt_pk_u8_f32 v22, v3, 1, v22
	v_cvt_pk_u8_f32 v23, v7, 1, v23
	v_cvt_pk_u8_f32 v24, v11, 1, v24
	v_cvt_pk_u8_f32 v25, v15, 1, v25
	v_cvt_pk_u8_f32 v22, v4, 2, v22
	v_cvt_pk_u8_f32 v23, v8, 2, v23
	v_cvt_pk_u8_f32 v24, v12, 2, v24
	v_cvt_pk_u8_f32 v25, v16, 2, v25
	v_cvt_pk_u8_f32 v22, v5, 3, v22
	v_cvt_pk_u8_f32 v23, v9, 3, v23
	v_cvt_pk_u8_f32 v24, v13, 3, v24
	v_cvt_pk_u8_f32 v25, v17, 3, v25
	global_store_dwordx4 v[0:1], v[22:25], off offset:1024 nt
	v_mul_f32_e32 v2, 0xbfb8aa3b, v130
	v_mul_f32_e32 v3, 0xbfb8aa3b, v131
	v_mul_f32_e32 v4, 0xbfb8aa3b, v132
	v_mul_f32_e32 v5, 0xbfb8aa3b, v133
	v_mul_f32_e32 v6, 0xbfb8aa3b, v126
	v_mul_f32_e32 v7, 0xbfb8aa3b, v127
	v_mul_f32_e32 v8, 0xbfb8aa3b, v128
	v_mul_f32_e32 v9, 0xbfb8aa3b, v129
	v_mul_f32_e32 v10, 0xbfb8aa3b, v122
	v_mul_f32_e32 v11, 0xbfb8aa3b, v123
	v_mul_f32_e32 v12, 0xbfb8aa3b, v124
	v_mul_f32_e32 v13, 0xbfb8aa3b, v125
	v_mul_f32_e32 v14, 0xbfb8aa3b, v118
	v_mul_f32_e32 v15, 0xbfb8aa3b, v119
	v_mul_f32_e32 v16, 0xbfb8aa3b, v120
	v_mul_f32_e32 v17, 0xbfb8aa3b, v121
	v_exp_f32_e32 v2, v2
	v_exp_f32_e32 v3, v3
	v_exp_f32_e32 v4, v4
	v_exp_f32_e32 v5, v5
	v_exp_f32_e32 v6, v6
	v_exp_f32_e32 v7, v7
	v_exp_f32_e32 v8, v8
	v_exp_f32_e32 v9, v9
	v_exp_f32_e32 v10, v10
	v_exp_f32_e32 v11, v11
	v_exp_f32_e32 v12, v12
	v_exp_f32_e32 v13, v13
	v_exp_f32_e32 v14, v14
	v_exp_f32_e32 v15, v15
	v_exp_f32_e32 v16, v16
	v_exp_f32_e32 v17, v17
	v_fma_f32 v2, v2, v217, v217 clamp
	v_fma_f32 v3, v3, v217, v217 clamp
	v_fma_f32 v4, v4, v217, v217 clamp
	v_fma_f32 v5, v5, v217, v217 clamp
	v_fma_f32 v6, v6, v217, v217 clamp
	v_fma_f32 v7, v7, v217, v217 clamp
	v_fma_f32 v8, v8, v217, v217 clamp
	v_fma_f32 v9, v9, v217, v217 clamp
	v_fma_f32 v10, v10, v217, v217 clamp
	v_fma_f32 v11, v11, v217, v217 clamp
	v_fma_f32 v12, v12, v217, v217 clamp
	v_fma_f32 v13, v13, v217, v217 clamp
	v_fma_f32 v14, v14, v217, v217 clamp
	v_fma_f32 v15, v15, v217, v217 clamp
	v_fma_f32 v16, v16, v217, v217 clamp
	v_fma_f32 v17, v17, v217, v217 clamp
	v_rcp_f32_e32 v2, v2
	v_rcp_f32_e32 v3, v3
	v_rcp_f32_e32 v4, v4
	v_rcp_f32_e32 v5, v5
	v_rcp_f32_e32 v6, v6
	v_rcp_f32_e32 v7, v7
	v_rcp_f32_e32 v8, v8
	v_rcp_f32_e32 v9, v9
	v_rcp_f32_e32 v10, v10
	v_rcp_f32_e32 v11, v11
	v_rcp_f32_e32 v12, v12
	v_rcp_f32_e32 v13, v13
	v_rcp_f32_e32 v14, v14
	v_rcp_f32_e32 v15, v15
	v_rcp_f32_e32 v16, v16
	v_rcp_f32_e32 v17, v17
	v_cvt_pk_u8_f32 v18, v2, 0, 0
	v_cvt_pk_u8_f32 v19, v6, 0, 0
	v_cvt_pk_u8_f32 v20, v10, 0, 0
	v_cvt_pk_u8_f32 v21, v14, 0, 0
	v_cvt_pk_u8_f32 v18, v3, 1, v18
	v_cvt_pk_u8_f32 v19, v7, 1, v19
	v_cvt_pk_u8_f32 v20, v11, 1, v20
	v_cvt_pk_u8_f32 v21, v15, 1, v21
	v_cvt_pk_u8_f32 v18, v4, 2, v18
	v_cvt_pk_u8_f32 v19, v8, 2, v19
	v_cvt_pk_u8_f32 v20, v12, 2, v20
	v_cvt_pk_u8_f32 v21, v16, 2, v21
	v_cvt_pk_u8_f32 v18, v5, 3, v18
	v_cvt_pk_u8_f32 v19, v9, 3, v19
	v_cvt_pk_u8_f32 v20, v13, 3, v20
	v_cvt_pk_u8_f32 v21, v17, 3, v21
	global_store_dwordx4 v[0:1], v[18:21], off offset:2048 nt
	v_mul_f32_e32 v2, 0xbfb8aa3b, v114
	v_mul_f32_e32 v3, 0xbfb8aa3b, v115
	v_mul_f32_e32 v4, 0xbfb8aa3b, v116
	v_mul_f32_e32 v5, 0xbfb8aa3b, v117
	v_mul_f32_e32 v6, 0xbfb8aa3b, v110
	v_mul_f32_e32 v7, 0xbfb8aa3b, v111
	v_mul_f32_e32 v8, 0xbfb8aa3b, v112
	v_mul_f32_e32 v9, 0xbfb8aa3b, v113
	v_mul_f32_e32 v10, 0xbfb8aa3b, v106
	v_mul_f32_e32 v11, 0xbfb8aa3b, v107
	v_mul_f32_e32 v12, 0xbfb8aa3b, v108
	v_mul_f32_e32 v13, 0xbfb8aa3b, v109
	v_mul_f32_e32 v14, 0xbfb8aa3b, v102
	v_mul_f32_e32 v15, 0xbfb8aa3b, v103
	v_mul_f32_e32 v16, 0xbfb8aa3b, v104
	v_mul_f32_e32 v17, 0xbfb8aa3b, v105
	v_exp_f32_e32 v2, v2
	v_exp_f32_e32 v3, v3
	v_exp_f32_e32 v4, v4
	v_exp_f32_e32 v5, v5
	v_exp_f32_e32 v6, v6
	v_exp_f32_e32 v7, v7
	v_exp_f32_e32 v8, v8
	v_exp_f32_e32 v9, v9
	v_exp_f32_e32 v10, v10
	v_exp_f32_e32 v11, v11
	v_exp_f32_e32 v12, v12
	v_exp_f32_e32 v13, v13
	v_exp_f32_e32 v14, v14
	v_exp_f32_e32 v15, v15
	v_exp_f32_e32 v16, v16
	v_exp_f32_e32 v17, v17
	v_fma_f32 v2, v2, v217, v217 clamp
	v_fma_f32 v3, v3, v217, v217 clamp
	v_fma_f32 v4, v4, v217, v217 clamp
	v_fma_f32 v5, v5, v217, v217 clamp
	v_fma_f32 v6, v6, v217, v217 clamp
	v_fma_f32 v7, v7, v217, v217 clamp
	v_fma_f32 v8, v8, v217, v217 clamp
	v_fma_f32 v9, v9, v217, v217 clamp
	v_fma_f32 v10, v10, v217, v217 clamp
	v_fma_f32 v11, v11, v217, v217 clamp
	v_fma_f32 v12, v12, v217, v217 clamp
	v_fma_f32 v13, v13, v217, v217 clamp
	v_fma_f32 v14, v14, v217, v217 clamp
	v_fma_f32 v15, v15, v217, v217 clamp
	v_fma_f32 v16, v16, v217, v217 clamp
	v_fma_f32 v17, v17, v217, v217 clamp
	v_rcp_f32_e32 v2, v2
	v_rcp_f32_e32 v3, v3
	v_rcp_f32_e32 v4, v4
	v_rcp_f32_e32 v5, v5
	v_rcp_f32_e32 v6, v6
	v_rcp_f32_e32 v7, v7
	v_rcp_f32_e32 v8, v8
	v_rcp_f32_e32 v9, v9
	v_rcp_f32_e32 v10, v10
	v_rcp_f32_e32 v11, v11
	v_rcp_f32_e32 v12, v12
	v_rcp_f32_e32 v13, v13
	v_rcp_f32_e32 v14, v14
	v_rcp_f32_e32 v15, v15
	v_rcp_f32_e32 v16, v16
	v_rcp_f32_e32 v17, v17
	v_cvt_pk_u8_f32 v22, v2, 0, 0
	v_cvt_pk_u8_f32 v23, v6, 0, 0
	v_cvt_pk_u8_f32 v24, v10, 0, 0
	v_cvt_pk_u8_f32 v25, v14, 0, 0
	v_cvt_pk_u8_f32 v22, v3, 1, v22
	v_cvt_pk_u8_f32 v23, v7, 1, v23
	v_cvt_pk_u8_f32 v24, v11, 1, v24
	v_cvt_pk_u8_f32 v25, v15, 1, v25
	v_cvt_pk_u8_f32 v22, v4, 2, v22
	v_cvt_pk_u8_f32 v23, v8, 2, v23
	v_cvt_pk_u8_f32 v24, v12, 2, v24
	v_cvt_pk_u8_f32 v25, v16, 2, v25
	v_cvt_pk_u8_f32 v22, v5, 3, v22
	v_cvt_pk_u8_f32 v23, v9, 3, v23
	v_cvt_pk_u8_f32 v24, v13, 3, v24
	v_cvt_pk_u8_f32 v25, v17, 3, v25
	global_store_dwordx4 v[0:1], v[22:25], off offset:3072 nt
	v_mul_f32_e32 v2, 0xbfb8aa3b, v98
	v_mul_f32_e32 v3, 0xbfb8aa3b, v99
	v_mul_f32_e32 v4, 0xbfb8aa3b, v100
	v_mul_f32_e32 v5, 0xbfb8aa3b, v101
	v_mul_f32_e32 v6, 0xbfb8aa3b, v94
	v_mul_f32_e32 v7, 0xbfb8aa3b, v95
	v_mul_f32_e32 v8, 0xbfb8aa3b, v96
	v_mul_f32_e32 v9, 0xbfb8aa3b, v97
	v_mul_f32_e32 v10, 0xbfb8aa3b, v90
	v_mul_f32_e32 v11, 0xbfb8aa3b, v91
	v_mul_f32_e32 v12, 0xbfb8aa3b, v92
	v_mul_f32_e32 v13, 0xbfb8aa3b, v93
	v_mul_f32_e32 v14, 0xbfb8aa3b, v86
	v_mul_f32_e32 v15, 0xbfb8aa3b, v87
	v_mul_f32_e32 v16, 0xbfb8aa3b, v88
	v_mul_f32_e32 v17, 0xbfb8aa3b, v89
	v_exp_f32_e32 v2, v2
	v_exp_f32_e32 v3, v3
	v_exp_f32_e32 v4, v4
	v_exp_f32_e32 v5, v5
	v_exp_f32_e32 v6, v6
	v_exp_f32_e32 v7, v7
	v_exp_f32_e32 v8, v8
	v_exp_f32_e32 v9, v9
	v_exp_f32_e32 v10, v10
	v_exp_f32_e32 v11, v11
	v_exp_f32_e32 v12, v12
	v_exp_f32_e32 v13, v13
	v_exp_f32_e32 v14, v14
	v_exp_f32_e32 v15, v15
	v_exp_f32_e32 v16, v16
	v_exp_f32_e32 v17, v17
	v_fma_f32 v2, v2, v217, v217 clamp
	v_fma_f32 v3, v3, v217, v217 clamp
	v_fma_f32 v4, v4, v217, v217 clamp
	v_fma_f32 v5, v5, v217, v217 clamp
	v_fma_f32 v6, v6, v217, v217 clamp
	v_fma_f32 v7, v7, v217, v217 clamp
	v_fma_f32 v8, v8, v217, v217 clamp
	v_fma_f32 v9, v9, v217, v217 clamp
	v_fma_f32 v10, v10, v217, v217 clamp
	v_fma_f32 v11, v11, v217, v217 clamp
	v_fma_f32 v12, v12, v217, v217 clamp
	v_fma_f32 v13, v13, v217, v217 clamp
	v_fma_f32 v14, v14, v217, v217 clamp
	v_fma_f32 v15, v15, v217, v217 clamp
	v_fma_f32 v16, v16, v217, v217 clamp
	v_fma_f32 v17, v17, v217, v217 clamp
	v_rcp_f32_e32 v2, v2
	v_rcp_f32_e32 v3, v3
	v_rcp_f32_e32 v4, v4
	v_rcp_f32_e32 v5, v5
	v_rcp_f32_e32 v6, v6
	v_rcp_f32_e32 v7, v7
	v_rcp_f32_e32 v8, v8
	v_rcp_f32_e32 v9, v9
	v_rcp_f32_e32 v10, v10
	v_rcp_f32_e32 v11, v11
	v_rcp_f32_e32 v12, v12
	v_rcp_f32_e32 v13, v13
	v_rcp_f32_e32 v14, v14
	v_rcp_f32_e32 v15, v15
	v_rcp_f32_e32 v16, v16
	v_rcp_f32_e32 v17, v17
	v_cvt_pk_u8_f32 v18, v2, 0, 0
	v_cvt_pk_u8_f32 v19, v6, 0, 0
	v_cvt_pk_u8_f32 v20, v10, 0, 0
	v_cvt_pk_u8_f32 v21, v14, 0, 0
	v_cvt_pk_u8_f32 v18, v3, 1, v18
	v_cvt_pk_u8_f32 v19, v7, 1, v19
	v_cvt_pk_u8_f32 v20, v11, 1, v20
	v_cvt_pk_u8_f32 v21, v15, 1, v21
	v_cvt_pk_u8_f32 v18, v4, 2, v18
	v_cvt_pk_u8_f32 v19, v8, 2, v19
	v_cvt_pk_u8_f32 v20, v12, 2, v20
	v_cvt_pk_u8_f32 v21, v16, 2, v21
	v_cvt_pk_u8_f32 v18, v5, 3, v18
	v_cvt_pk_u8_f32 v19, v9, 3, v19
	v_cvt_pk_u8_f32 v20, v13, 3, v20
	v_cvt_pk_u8_f32 v21, v17, 3, v21
	global_store_dwordx4 v[26:27], v[18:21], off nt
	v_mul_f32_e32 v2, 0xbfb8aa3b, v82
	v_mul_f32_e32 v3, 0xbfb8aa3b, v83
	v_mul_f32_e32 v4, 0xbfb8aa3b, v84
	v_mul_f32_e32 v5, 0xbfb8aa3b, v85
	v_mul_f32_e32 v6, 0xbfb8aa3b, v78
	v_mul_f32_e32 v7, 0xbfb8aa3b, v79
	v_mul_f32_e32 v8, 0xbfb8aa3b, v80
	v_mul_f32_e32 v9, 0xbfb8aa3b, v81
	v_mul_f32_e32 v10, 0xbfb8aa3b, v74
	v_mul_f32_e32 v11, 0xbfb8aa3b, v75
	v_mul_f32_e32 v12, 0xbfb8aa3b, v76
	v_mul_f32_e32 v13, 0xbfb8aa3b, v77
	v_mul_f32_e32 v14, 0xbfb8aa3b, v70
	v_mul_f32_e32 v15, 0xbfb8aa3b, v71
	v_mul_f32_e32 v16, 0xbfb8aa3b, v72
	v_mul_f32_e32 v17, 0xbfb8aa3b, v73
	v_exp_f32_e32 v2, v2
	v_exp_f32_e32 v3, v3
	v_exp_f32_e32 v4, v4
	v_exp_f32_e32 v5, v5
	v_exp_f32_e32 v6, v6
	v_exp_f32_e32 v7, v7
	v_exp_f32_e32 v8, v8
	v_exp_f32_e32 v9, v9
	v_exp_f32_e32 v10, v10
	v_exp_f32_e32 v11, v11
	v_exp_f32_e32 v12, v12
	v_exp_f32_e32 v13, v13
	v_exp_f32_e32 v14, v14
	v_exp_f32_e32 v15, v15
	v_exp_f32_e32 v16, v16
	v_exp_f32_e32 v17, v17
	v_fma_f32 v2, v2, v217, v217 clamp
	v_fma_f32 v3, v3, v217, v217 clamp
	v_fma_f32 v4, v4, v217, v217 clamp
	v_fma_f32 v5, v5, v217, v217 clamp
	v_fma_f32 v6, v6, v217, v217 clamp
	v_fma_f32 v7, v7, v217, v217 clamp
	v_fma_f32 v8, v8, v217, v217 clamp
	v_fma_f32 v9, v9, v217, v217 clamp
	v_fma_f32 v10, v10, v217, v217 clamp
	v_fma_f32 v11, v11, v217, v217 clamp
	v_fma_f32 v12, v12, v217, v217 clamp
	v_fma_f32 v13, v13, v217, v217 clamp
	v_fma_f32 v14, v14, v217, v217 clamp
	v_fma_f32 v15, v15, v217, v217 clamp
	v_fma_f32 v16, v16, v217, v217 clamp
	v_fma_f32 v17, v17, v217, v217 clamp
	v_rcp_f32_e32 v2, v2
	v_rcp_f32_e32 v3, v3
	v_rcp_f32_e32 v4, v4
	v_rcp_f32_e32 v5, v5
	v_rcp_f32_e32 v6, v6
	v_rcp_f32_e32 v7, v7
	v_rcp_f32_e32 v8, v8
	v_rcp_f32_e32 v9, v9
	v_rcp_f32_e32 v10, v10
	v_rcp_f32_e32 v11, v11
	v_rcp_f32_e32 v12, v12
	v_rcp_f32_e32 v13, v13
	v_rcp_f32_e32 v14, v14
	v_rcp_f32_e32 v15, v15
	v_rcp_f32_e32 v16, v16
	v_rcp_f32_e32 v17, v17
	v_cvt_pk_u8_f32 v22, v2, 0, 0
	v_cvt_pk_u8_f32 v23, v6, 0, 0
	v_cvt_pk_u8_f32 v24, v10, 0, 0
	v_cvt_pk_u8_f32 v25, v14, 0, 0
	v_cvt_pk_u8_f32 v22, v3, 1, v22
	v_cvt_pk_u8_f32 v23, v7, 1, v23
	v_cvt_pk_u8_f32 v24, v11, 1, v24
	v_cvt_pk_u8_f32 v25, v15, 1, v25
	v_cvt_pk_u8_f32 v22, v4, 2, v22
	v_cvt_pk_u8_f32 v23, v8, 2, v23
	v_cvt_pk_u8_f32 v24, v12, 2, v24
	v_cvt_pk_u8_f32 v25, v16, 2, v25
	v_cvt_pk_u8_f32 v22, v5, 3, v22
	v_cvt_pk_u8_f32 v23, v9, 3, v23
	v_cvt_pk_u8_f32 v24, v13, 3, v24
	v_cvt_pk_u8_f32 v25, v17, 3, v25
	global_store_dwordx4 v[26:27], v[22:25], off offset:1024 nt
	v_mul_f32_e32 v2, 0xbfb8aa3b, v66
	v_mul_f32_e32 v3, 0xbfb8aa3b, v67
	v_mul_f32_e32 v4, 0xbfb8aa3b, v68
	v_mul_f32_e32 v5, 0xbfb8aa3b, v69
	v_mul_f32_e32 v6, 0xbfb8aa3b, v62
	v_mul_f32_e32 v7, 0xbfb8aa3b, v63
	v_mul_f32_e32 v8, 0xbfb8aa3b, v64
	v_mul_f32_e32 v9, 0xbfb8aa3b, v65
	v_mul_f32_e32 v10, 0xbfb8aa3b, v58
	v_mul_f32_e32 v11, 0xbfb8aa3b, v59
	v_mul_f32_e32 v12, 0xbfb8aa3b, v60
	v_mul_f32_e32 v13, 0xbfb8aa3b, v61
	v_mul_f32_e32 v14, 0xbfb8aa3b, v54
	v_mul_f32_e32 v15, 0xbfb8aa3b, v55
	v_mul_f32_e32 v16, 0xbfb8aa3b, v56
	v_mul_f32_e32 v17, 0xbfb8aa3b, v57
	v_exp_f32_e32 v2, v2
	v_exp_f32_e32 v3, v3
	v_exp_f32_e32 v4, v4
	v_exp_f32_e32 v5, v5
	v_exp_f32_e32 v6, v6
	v_exp_f32_e32 v7, v7
	v_exp_f32_e32 v8, v8
	v_exp_f32_e32 v9, v9
	v_exp_f32_e32 v10, v10
	v_exp_f32_e32 v11, v11
	v_exp_f32_e32 v12, v12
	v_exp_f32_e32 v13, v13
	v_exp_f32_e32 v14, v14
	v_exp_f32_e32 v15, v15
	v_exp_f32_e32 v16, v16
	v_exp_f32_e32 v17, v17
	v_fma_f32 v2, v2, v217, v217 clamp
	v_fma_f32 v3, v3, v217, v217 clamp
	v_fma_f32 v4, v4, v217, v217 clamp
	v_fma_f32 v5, v5, v217, v217 clamp
	v_fma_f32 v6, v6, v217, v217 clamp
	v_fma_f32 v7, v7, v217, v217 clamp
	v_fma_f32 v8, v8, v217, v217 clamp
	v_fma_f32 v9, v9, v217, v217 clamp
	v_fma_f32 v10, v10, v217, v217 clamp
	v_fma_f32 v11, v11, v217, v217 clamp
	v_fma_f32 v12, v12, v217, v217 clamp
	v_fma_f32 v13, v13, v217, v217 clamp
	v_fma_f32 v14, v14, v217, v217 clamp
	v_fma_f32 v15, v15, v217, v217 clamp
	v_fma_f32 v16, v16, v217, v217 clamp
	v_fma_f32 v17, v17, v217, v217 clamp
	v_rcp_f32_e32 v2, v2
	v_rcp_f32_e32 v3, v3
	v_rcp_f32_e32 v4, v4
	v_rcp_f32_e32 v5, v5
	v_rcp_f32_e32 v6, v6
	v_rcp_f32_e32 v7, v7
	v_rcp_f32_e32 v8, v8
	v_rcp_f32_e32 v9, v9
	v_rcp_f32_e32 v10, v10
	v_rcp_f32_e32 v11, v11
	v_rcp_f32_e32 v12, v12
	v_rcp_f32_e32 v13, v13
	v_rcp_f32_e32 v14, v14
	v_rcp_f32_e32 v15, v15
	v_rcp_f32_e32 v16, v16
	v_rcp_f32_e32 v17, v17
	v_cvt_pk_u8_f32 v18, v2, 0, 0
	v_cvt_pk_u8_f32 v19, v6, 0, 0
	v_cvt_pk_u8_f32 v20, v10, 0, 0
	v_cvt_pk_u8_f32 v21, v14, 0, 0
	v_cvt_pk_u8_f32 v18, v3, 1, v18
	v_cvt_pk_u8_f32 v19, v7, 1, v19
	v_cvt_pk_u8_f32 v20, v11, 1, v20
	v_cvt_pk_u8_f32 v21, v15, 1, v21
	v_cvt_pk_u8_f32 v18, v4, 2, v18
	v_cvt_pk_u8_f32 v19, v8, 2, v19
	v_cvt_pk_u8_f32 v20, v12, 2, v20
	v_cvt_pk_u8_f32 v21, v16, 2, v21
	v_cvt_pk_u8_f32 v18, v5, 3, v18
	v_cvt_pk_u8_f32 v19, v9, 3, v19
	v_cvt_pk_u8_f32 v20, v13, 3, v20
	v_cvt_pk_u8_f32 v21, v17, 3, v21
	global_store_dwordx4 v[26:27], v[18:21], off offset:2048 nt
	v_mul_f32_e32 v2, 0xbfb8aa3b, v50
	v_mul_f32_e32 v3, 0xbfb8aa3b, v51
	v_mul_f32_e32 v4, 0xbfb8aa3b, v52
	v_mul_f32_e32 v5, 0xbfb8aa3b, v53
	v_mul_f32_e32 v6, 0xbfb8aa3b, v46
	v_mul_f32_e32 v7, 0xbfb8aa3b, v47
	v_mul_f32_e32 v8, 0xbfb8aa3b, v48
	v_mul_f32_e32 v9, 0xbfb8aa3b, v49
	v_mul_f32_e32 v10, 0xbfb8aa3b, v42
	v_mul_f32_e32 v11, 0xbfb8aa3b, v43
	v_mul_f32_e32 v12, 0xbfb8aa3b, v44
	v_mul_f32_e32 v13, 0xbfb8aa3b, v45
	v_mul_f32_e32 v14, 0xbfb8aa3b, v38
	v_mul_f32_e32 v15, 0xbfb8aa3b, v39
	v_mul_f32_e32 v16, 0xbfb8aa3b, v40
	v_mul_f32_e32 v17, 0xbfb8aa3b, v41
	v_exp_f32_e32 v2, v2
	v_exp_f32_e32 v3, v3
	v_exp_f32_e32 v4, v4
	v_exp_f32_e32 v5, v5
	v_exp_f32_e32 v6, v6
	v_exp_f32_e32 v7, v7
	v_exp_f32_e32 v8, v8
	v_exp_f32_e32 v9, v9
	v_exp_f32_e32 v10, v10
	v_exp_f32_e32 v11, v11
	v_exp_f32_e32 v12, v12
	v_exp_f32_e32 v13, v13
	v_exp_f32_e32 v14, v14
	v_exp_f32_e32 v15, v15
	v_exp_f32_e32 v16, v16
	v_exp_f32_e32 v17, v17
	v_fma_f32 v2, v2, v217, v217 clamp
	v_fma_f32 v3, v3, v217, v217 clamp
	v_fma_f32 v4, v4, v217, v217 clamp
	v_fma_f32 v5, v5, v217, v217 clamp
	v_fma_f32 v6, v6, v217, v217 clamp
	v_fma_f32 v7, v7, v217, v217 clamp
	v_fma_f32 v8, v8, v217, v217 clamp
	v_fma_f32 v9, v9, v217, v217 clamp
	v_fma_f32 v10, v10, v217, v217 clamp
	v_fma_f32 v11, v11, v217, v217 clamp
	v_fma_f32 v12, v12, v217, v217 clamp
	v_fma_f32 v13, v13, v217, v217 clamp
	v_fma_f32 v14, v14, v217, v217 clamp
	v_fma_f32 v15, v15, v217, v217 clamp
	v_fma_f32 v16, v16, v217, v217 clamp
	v_fma_f32 v17, v17, v217, v217 clamp
	v_rcp_f32_e32 v2, v2
	v_rcp_f32_e32 v3, v3
	v_rcp_f32_e32 v4, v4
	v_rcp_f32_e32 v5, v5
	v_rcp_f32_e32 v6, v6
	v_rcp_f32_e32 v7, v7
	v_rcp_f32_e32 v8, v8
	v_rcp_f32_e32 v9, v9
	v_rcp_f32_e32 v10, v10
	v_rcp_f32_e32 v11, v11
	v_rcp_f32_e32 v12, v12
	v_rcp_f32_e32 v13, v13
	v_rcp_f32_e32 v14, v14
	v_rcp_f32_e32 v15, v15
	v_rcp_f32_e32 v16, v16
	v_rcp_f32_e32 v17, v17
	v_cvt_pk_u8_f32 v22, v2, 0, 0
	v_cvt_pk_u8_f32 v23, v6, 0, 0
	v_cvt_pk_u8_f32 v24, v10, 0, 0
	v_cvt_pk_u8_f32 v25, v14, 0, 0
	v_cvt_pk_u8_f32 v22, v3, 1, v22
	v_cvt_pk_u8_f32 v23, v7, 1, v23
	v_cvt_pk_u8_f32 v24, v11, 1, v24
	v_cvt_pk_u8_f32 v25, v15, 1, v25
	v_cvt_pk_u8_f32 v22, v4, 2, v22
	v_cvt_pk_u8_f32 v23, v8, 2, v23
	v_cvt_pk_u8_f32 v24, v12, 2, v24
	v_cvt_pk_u8_f32 v25, v16, 2, v25
	v_cvt_pk_u8_f32 v22, v5, 3, v22
	v_cvt_pk_u8_f32 v23, v9, 3, v23
	v_cvt_pk_u8_f32 v24, v13, 3, v24
	v_cvt_pk_u8_f32 v25, v17, 3, v25
	global_store_dwordx4 v[26:27], v[22:25], off offset:3072 nt
	s_andn2_b64 vcc, exec, s[30:31]
	s_mov_b64 s[8:9], -1
	s_cbranch_vccnz .LBB0_473
	s_branch .LBB0_539

.LBB0_520:
	s_cmp_lt_i32 s72, 3
	s_cbranch_scc1 .Lpxa_gen_b
	s_add_i32 s0, s72, -9
	s_cmp_lt_u32 s0, 2
	s_cbranch_scc1 .Lpxa_gen_b
	s_lshl_b32 s0, s73, 8
	s_add_i32 s0, s0, s63
	v_or_b32_e32 v202, s0, v204
	s_lshl_b32 s10, s72, 8
	s_mov_b32 s11, 0
	v_lshl_add_u64 v[198:199], s[10:11], 1, v[188:189]
	v_mov_b32_e32 v203, 0
	v_lshlrev_b64 v[18:19], 13, v[202:203]
	v_lshl_add_u64 v[22:23], v[198:199], 0, v[18:19]
	v_cvt_pk_bf16_f32 v0, v162, v163
	v_cvt_pk_bf16_f32 v1, v164, v165
	v_cvt_pk_bf16_f32 v2, v158, v159
	v_cvt_pk_bf16_f32 v3, v160, v161
	global_store_dwordx4 v[22:23], v[0:3], off
	v_cvt_pk_bf16_f32 v4, v154, v155
	v_cvt_pk_bf16_f32 v5, v156, v157
	v_cvt_pk_bf16_f32 v6, v150, v151
	v_cvt_pk_bf16_f32 v7, v152, v153
	global_store_dwordx4 v[22:23], v[4:7], off offset:256
	s_mov_b32 s8, 0x20000
	s_mov_b32 s9, 0
	v_lshl_add_u64 v[26:27], v[22:23], 0, s[8:9]
	v_cvt_pk_bf16_f32 v8, v146, v147
	v_cvt_pk_bf16_f32 v9, v148, v149
	v_cvt_pk_bf16_f32 v10, v142, v143
	v_cvt_pk_bf16_f32 v11, v144, v145
	global_store_dwordx4 v[26:27], v[8:11], off
	v_cvt_pk_bf16_f32 v12, v138, v139
	v_cvt_pk_bf16_f32 v13, v140, v141
	v_cvt_pk_bf16_f32 v14, v134, v135
	v_cvt_pk_bf16_f32 v15, v136, v137
	global_store_dwordx4 v[26:27], v[12:15], off offset:256
	s_mov_b32 s8, 0x40000
	s_mov_b32 s9, 0
	v_lshl_add_u64 v[28:29], v[22:23], 0, s[8:9]
	v_cvt_pk_bf16_f32 v0, v130, v131
	v_cvt_pk_bf16_f32 v1, v132, v133
	v_cvt_pk_bf16_f32 v2, v126, v127
	v_cvt_pk_bf16_f32 v3, v128, v129
	global_store_dwordx4 v[28:29], v[0:3], off
	v_cvt_pk_bf16_f32 v4, v122, v123
	v_cvt_pk_bf16_f32 v5, v124, v125
	v_cvt_pk_bf16_f32 v6, v118, v119
	v_cvt_pk_bf16_f32 v7, v120, v121
	global_store_dwordx4 v[28:29], v[4:7], off offset:256
	s_mov_b32 s8, 0x60000
	s_mov_b32 s9, 0
	v_lshl_add_u64 v[24:25], v[22:23], 0, s[8:9]
	v_cvt_pk_bf16_f32 v8, v114, v115
	v_cvt_pk_bf16_f32 v9, v116, v117
	v_cvt_pk_bf16_f32 v10, v110, v111
	v_cvt_pk_bf16_f32 v11, v112, v113
	global_store_dwordx4 v[24:25], v[8:11], off
	v_cvt_pk_bf16_f32 v12, v106, v107
	v_cvt_pk_bf16_f32 v13, v108, v109
	v_cvt_pk_bf16_f32 v14, v102, v103
	v_cvt_pk_bf16_f32 v15, v104, v105
	global_store_dwordx4 v[24:25], v[12:15], off offset:256
	s_mov_b32 s8, 0x100000
	s_mov_b32 s9, 0
	v_lshl_add_u64 v[26:27], v[22:23], 0, s[8:9]
	v_cvt_pk_bf16_f32 v0, v98, v99
	v_cvt_pk_bf16_f32 v1, v100, v101
	v_cvt_pk_bf16_f32 v2, v94, v95
	v_cvt_pk_bf16_f32 v3, v96, v97
	global_store_dwordx4 v[26:27], v[0:3], off
	v_cvt_pk_bf16_f32 v4, v90, v91
	v_cvt_pk_bf16_f32 v5, v92, v93
	v_cvt_pk_bf16_f32 v6, v86, v87
	v_cvt_pk_bf16_f32 v7, v88, v89
	global_store_dwordx4 v[26:27], v[4:7], off offset:256
	s_mov_b32 s8, 0x120000
	s_mov_b32 s9, 0
	v_lshl_add_u64 v[28:29], v[22:23], 0, s[8:9]
	v_cvt_pk_bf16_f32 v8, v82, v83
	v_cvt_pk_bf16_f32 v9, v84, v85
	v_cvt_pk_bf16_f32 v10, v78, v79
	v_cvt_pk_bf16_f32 v11, v80, v81
	global_store_dwordx4 v[28:29], v[8:11], off
	v_cvt_pk_bf16_f32 v12, v74, v75
	v_cvt_pk_bf16_f32 v13, v76, v77
	v_cvt_pk_bf16_f32 v14, v70, v71
	v_cvt_pk_bf16_f32 v15, v72, v73
	global_store_dwordx4 v[28:29], v[12:15], off offset:256
	s_mov_b32 s8, 0x140000
	s_mov_b32 s9, 0
	v_lshl_add_u64 v[24:25], v[22:23], 0, s[8:9]
	v_cvt_pk_bf16_f32 v0, v66, v67
	v_cvt_pk_bf16_f32 v1, v68, v69
	v_cvt_pk_bf16_f32 v2, v62, v63
	v_cvt_pk_bf16_f32 v3, v64, v65
	global_store_dwordx4 v[24:25], v[0:3], off
	v_cvt_pk_bf16_f32 v4, v58, v59
	v_cvt_pk_bf16_f32 v5, v60, v61
	v_cvt_pk_bf16_f32 v6, v54, v55
	v_cvt_pk_bf16_f32 v7, v56, v57
	global_store_dwordx4 v[24:25], v[4:7], off offset:256
	s_mov_b32 s8, 0x160000
	s_mov_b32 s9, 0
	v_lshl_add_u64 v[26:27], v[22:23], 0, s[8:9]
	v_cvt_pk_bf16_f32 v8, v50, v51
	v_cvt_pk_bf16_f32 v9, v52, v53
	v_cvt_pk_bf16_f32 v10, v46, v47
	v_cvt_pk_bf16_f32 v11, v48, v49
	global_store_dwordx4 v[26:27], v[8:11], off
	v_cvt_pk_bf16_f32 v12, v42, v43
	v_cvt_pk_bf16_f32 v13, v44, v45
	v_cvt_pk_bf16_f32 v14, v38, v39
	v_cvt_pk_bf16_f32 v15, v40, v41
	global_store_dwordx4 v[26:27], v[12:15], off offset:256
	s_branch .LBB0_538
